# adds: K-loop LDS-DMA loads use SGPR base + 32-bit VGPR offset (16 v_lshl_add_u64 per two K-tiles removed)
# speedup vs baseline: 1.4919x; 1.0040x over previous
.LBB0_619:
	s_ashr_i32 s39, s38, 31
	s_lshl_b64 s[2:3], s[38:39], 19
	s_add_u32 s40, s58, s2
	s_addc_u32 s41, s59, s3
	s_and_b64 s[2:3], s[36:37], exec
	s_cselect_b32 s11, s41, s31
	s_cselect_b32 s18, s40, s30
	s_ashr_i32 s13, s12, 31
	s_lshl_b64 s[2:3], s[12:13], 19
	s_add_u32 s42, s6, s2
	s_addc_u32 s43, s7, s3
	s_and_b64 s[2:3], s[36:37], exec
	s_cselect_b32 s13, s43, s17
	s_cselect_b32 s19, s42, s16
	s_add_u32 s30, s30, 0x40080
	s_addc_u32 s31, s31, 0
	s_add_u32 s28, s16, 0x100
	s_addc_u32 s29, s17, 0
	s_mov_b32 s39, -2
	s_add_u32 s2, s30, 0xfffc0080
	s_addc_u32 s3, s31, -1
	s_add_i32 s94, 32, 0x10000
	v_add_u32_e32 v131, s94, v145
	ds_read_b128 v[170:173], v131
	ds_read_b128 v[174:177], v131 offset:1024
	ds_read_b128 v[182:185], v131 offset:2048
	ds_read_b128 v[186:189], v131 offset:3072
	s_cmp_eq_u32 s39, 12
	s_cselect_b32 s3, s11, s3
	s_cselect_b32 s2, s18, s2
	s_cselect_b32 s17, s13, s29
	s_cselect_b32 s16, s19, s28
	s_add_i32 m0, s35, 0xc000
	ds_read_b128 v[190:193], v151
	ds_read_b128 v[194:197], v151 offset:1024
	ds_read_b128 v[198:201], v151 offset:2048
	ds_read_b128 v[202:205], v151 offset:3072
	ds_read_b128 v[206:209], v151 offset:4096
	ds_read_b128 v[210:213], v151 offset:5120
	ds_read_b128 v[214:217], v151 offset:6144
	ds_read_b128 v[218:221], v151 offset:7168
	global_load_lds_dwordx4 v140, s[30:31]
	s_add_i32 m0, s35, 0xe000
	s_nop 0
	global_load_lds_dwordx4 v142, s[30:31]
	s_waitcnt lgkmcnt(8)
	s_barrier
	s_waitcnt lgkmcnt(0)
	s_waitcnt lgkmcnt(0)
	v_mfma_f32_16x16x32_bf16 v[126:129], v[170:173], v[190:193], 0
	v_mfma_f32_16x16x32_bf16 v[122:125], v[182:185], v[190:193], 0
	v_mfma_f32_16x16x32_bf16 v[110:113], v[170:173], v[198:201], 0
	v_mfma_f32_16x16x32_bf16 v[106:109], v[182:185], v[198:201], 0
	v_mfma_f32_16x16x32_bf16 v[94:97], v[170:173], v[206:209], 0
	v_mfma_f32_16x16x32_bf16 v[90:93], v[182:185], v[206:209], 0
	v_mfma_f32_16x16x32_bf16 v[78:81], v[170:173], v[214:217], 0
	v_mfma_f32_16x16x32_bf16 v[74:77], v[182:185], v[214:217], 0
	v_mfma_f32_16x16x32_bf16 v[126:129], v[174:177], v[194:197], v[126:129]
	v_mfma_f32_16x16x32_bf16 v[122:125], v[186:189], v[194:197], v[122:125]
	v_mfma_f32_16x16x32_bf16 v[110:113], v[174:177], v[202:205], v[110:113]
	v_mfma_f32_16x16x32_bf16 v[106:109], v[186:189], v[202:205], v[106:109]
	v_mfma_f32_16x16x32_bf16 v[94:97], v[174:177], v[210:213], v[94:97]
	v_mfma_f32_16x16x32_bf16 v[90:93], v[186:189], v[210:213], v[90:93]
	v_mfma_f32_16x16x32_bf16 v[78:81], v[174:177], v[218:221], v[78:81]
	v_mfma_f32_16x16x32_bf16 v[74:77], v[186:189], v[218:221], v[74:77]
	s_barrier
	s_add_i32 vcc_lo, 32, 0x14000
	s_add_i32 s94, s94, s5
	v_add_u32_e32 v131, vcc_lo, v145
	s_mov_b32 m0, s94
	ds_read_b128 v[222:225], v131
	ds_read_b128 v[226:229], v131 offset:1024
	ds_read_b128 v[230:233], v131 offset:2048
	ds_read_b128 v[234:237], v131 offset:3072
	global_load_lds_dwordx4 v154, s[16:17]
	s_add_i32 m0, s94, 0x2000
	s_nop 0
	global_load_lds_dwordx4 v138, s[16:17]
	s_barrier
	s_waitcnt lgkmcnt(0)
	s_waitcnt lgkmcnt(0)
	v_mfma_f32_16x16x32_bf16 v[118:121], v[222:225], v[190:193], 0
	v_mfma_f32_16x16x32_bf16 v[114:117], v[230:233], v[190:193], 0
	v_mfma_f32_16x16x32_bf16 v[102:105], v[222:225], v[198:201], 0
	v_mfma_f32_16x16x32_bf16 v[98:101], v[230:233], v[198:201], 0
	v_mfma_f32_16x16x32_bf16 v[86:89], v[222:225], v[206:209], 0
	v_mfma_f32_16x16x32_bf16 v[82:85], v[230:233], v[206:209], 0
	v_mfma_f32_16x16x32_bf16 v[70:73], v[222:225], v[214:217], 0
	v_mfma_f32_16x16x32_bf16 v[66:69], v[230:233], v[214:217], 0
	v_mfma_f32_16x16x32_bf16 v[118:121], v[226:229], v[194:197], v[118:121]
	v_mfma_f32_16x16x32_bf16 v[114:117], v[234:237], v[194:197], v[114:117]
	v_mfma_f32_16x16x32_bf16 v[102:105], v[226:229], v[202:205], v[102:105]
	v_mfma_f32_16x16x32_bf16 v[98:101], v[234:237], v[202:205], v[98:101]
	v_mfma_f32_16x16x32_bf16 v[86:89], v[226:229], v[210:213], v[86:89]
	v_mfma_f32_16x16x32_bf16 v[82:85], v[234:237], v[210:213], v[82:85]
	v_mfma_f32_16x16x32_bf16 v[70:73], v[226:229], v[218:221], v[70:73]
	v_mfma_f32_16x16x32_bf16 v[66:69], v[234:237], v[218:221], v[66:69]
	s_mov_b32 m0, s35
	s_mov_b64 s[98:99], s[2:3]
	s_barrier
	ds_read_b128 v[190:193], v151 offset:16384
	ds_read_b128 v[194:197], v151 offset:17408
	ds_read_b128 v[198:201], v151 offset:18432
	ds_read_b128 v[202:205], v151 offset:19456
	ds_read_b128 v[206:209], v151 offset:20480
	ds_read_b128 v[210:213], v151 offset:21504
	ds_read_b128 v[214:217], v151 offset:22528
	ds_read_b128 v[218:221], v151 offset:23552
	global_load_lds_dwordx4 v134, s[2:3]
	s_mov_b32 m0, s14
	s_nop 0
	global_load_lds_dwordx4 v136, s[2:3]
	s_barrier
	s_waitcnt lgkmcnt(0)
	s_waitcnt lgkmcnt(0)
	v_mfma_f32_16x16x32_bf16 v[62:65], v[170:173], v[190:193], 0
	v_mfma_f32_16x16x32_bf16 v[58:61], v[182:185], v[190:193], 0
	v_mfma_f32_16x16x32_bf16 v[46:49], v[170:173], v[198:201], 0
	v_mfma_f32_16x16x32_bf16 v[42:45], v[182:185], v[198:201], 0
	v_mfma_f32_16x16x32_bf16 v[30:33], v[170:173], v[206:209], 0
	v_mfma_f32_16x16x32_bf16 v[26:29], v[182:185], v[206:209], 0
	v_mfma_f32_16x16x32_bf16 v[14:17], v[170:173], v[214:217], 0
	v_mfma_f32_16x16x32_bf16 v[10:13], v[182:185], v[214:217], 0
	v_mfma_f32_16x16x32_bf16 v[62:65], v[174:177], v[194:197], v[62:65]
	v_mfma_f32_16x16x32_bf16 v[58:61], v[186:189], v[194:197], v[58:61]
	v_mfma_f32_16x16x32_bf16 v[46:49], v[174:177], v[202:205], v[46:49]
	v_mfma_f32_16x16x32_bf16 v[42:45], v[186:189], v[202:205], v[42:45]
	v_mfma_f32_16x16x32_bf16 v[30:33], v[174:177], v[210:213], v[30:33]
	v_mfma_f32_16x16x32_bf16 v[26:29], v[186:189], v[210:213], v[26:29]
	v_mfma_f32_16x16x32_bf16 v[14:17], v[174:177], v[218:221], v[14:17]
	v_mfma_f32_16x16x32_bf16 v[10:13], v[186:189], v[218:221], v[10:13]
	s_barrier
	s_add_u32 s94, s16, 0x40000
	s_addc_u32 s95, s17, 0
	s_add_i32 vcc_lo, vcc_lo, s5
	s_mov_b32 m0, vcc_lo
	s_nop 0
	global_load_lds_dwordx4 v154, s[94:95]
	s_add_i32 m0, vcc_lo, 0x2000
	s_nop 0
	global_load_lds_dwordx4 v138, s[94:95]
	s_waitcnt vmcnt(6)
	s_barrier
	v_mfma_f32_16x16x32_bf16 v[54:57], v[222:225], v[190:193], 0
	v_mfma_f32_16x16x32_bf16 v[50:53], v[230:233], v[190:193], 0
	v_mfma_f32_16x16x32_bf16 v[38:41], v[222:225], v[198:201], 0
	v_mfma_f32_16x16x32_bf16 v[34:37], v[230:233], v[198:201], 0
	v_mfma_f32_16x16x32_bf16 v[22:25], v[222:225], v[206:209], 0
	v_mfma_f32_16x16x32_bf16 v[18:21], v[230:233], v[206:209], 0
	v_mfma_f32_16x16x32_bf16 v[6:9], v[222:225], v[214:217], 0
	v_mfma_f32_16x16x32_bf16 v[2:5], v[230:233], v[214:217], 0
	v_mfma_f32_16x16x32_bf16 v[54:57], v[226:229], v[194:197], v[54:57]
	v_mfma_f32_16x16x32_bf16 v[50:53], v[234:237], v[194:197], v[50:53]
	v_mfma_f32_16x16x32_bf16 v[38:41], v[226:229], v[202:205], v[38:41]
	v_mfma_f32_16x16x32_bf16 v[34:37], v[234:237], v[202:205], v[34:37]
	v_mfma_f32_16x16x32_bf16 v[22:25], v[226:229], v[210:213], v[22:25]
	v_mfma_f32_16x16x32_bf16 v[18:21], v[234:237], v[210:213], v[18:21]
	v_mfma_f32_16x16x32_bf16 v[6:9], v[226:229], v[218:221], v[6:9]
	v_mfma_f32_16x16x32_bf16 v[2:5], v[234:237], v[218:221], v[2:5]
	s_add_i32 s94, 32, 0x18000
	v_add_u32_e32 v131, s94, v145
	s_barrier
	ds_read_b128 v[170:173], v131
	ds_read_b128 v[174:177], v131 offset:1024
	ds_read_b128 v[182:185], v131 offset:2048
	ds_read_b128 v[186:189], v131 offset:3072
	s_add_u32 s2, s2, 0x40000
	s_addc_u32 s3, s3, 0
	s_mov_b32 m0, s4
	ds_read_b128 v[190:193], v151 offset:32768
	ds_read_b128 v[194:197], v151 offset:33792
	ds_read_b128 v[198:201], v151 offset:34816
	ds_read_b128 v[202:205], v151 offset:35840
	ds_read_b128 v[206:209], v151 offset:36864
	ds_read_b128 v[210:213], v151 offset:37888
	ds_read_b128 v[214:217], v151 offset:38912
	ds_read_b128 v[218:221], v151 offset:39936
	global_load_lds_dwordx4 v134, s[2:3]
	s_mov_b32 m0, s20
	s_nop 0
	global_load_lds_dwordx4 v136, s[2:3]
	s_waitcnt lgkmcnt(8)
	s_barrier
	s_waitcnt lgkmcnt(0)
	s_waitcnt lgkmcnt(0)
	v_mfma_f32_16x16x32_bf16 v[126:129], v[170:173], v[190:193], v[126:129]
	v_mfma_f32_16x16x32_bf16 v[122:125], v[182:185], v[190:193], v[122:125]
	v_mfma_f32_16x16x32_bf16 v[110:113], v[170:173], v[198:201], v[110:113]
	v_mfma_f32_16x16x32_bf16 v[106:109], v[182:185], v[198:201], v[106:109]
	v_mfma_f32_16x16x32_bf16 v[94:97], v[170:173], v[206:209], v[94:97]
	v_mfma_f32_16x16x32_bf16 v[90:93], v[182:185], v[206:209], v[90:93]
	v_mfma_f32_16x16x32_bf16 v[78:81], v[170:173], v[214:217], v[78:81]
	v_mfma_f32_16x16x32_bf16 v[74:77], v[182:185], v[214:217], v[74:77]
	v_mfma_f32_16x16x32_bf16 v[126:129], v[174:177], v[194:197], v[126:129]
	v_mfma_f32_16x16x32_bf16 v[122:125], v[186:189], v[194:197], v[122:125]
	v_mfma_f32_16x16x32_bf16 v[110:113], v[174:177], v[202:205], v[110:113]
	v_mfma_f32_16x16x32_bf16 v[106:109], v[186:189], v[202:205], v[106:109]
	v_mfma_f32_16x16x32_bf16 v[94:97], v[174:177], v[210:213], v[94:97]
	v_mfma_f32_16x16x32_bf16 v[90:93], v[186:189], v[210:213], v[90:93]
	v_mfma_f32_16x16x32_bf16 v[78:81], v[174:177], v[218:221], v[78:81]
	v_mfma_f32_16x16x32_bf16 v[74:77], v[186:189], v[218:221], v[74:77]
	s_barrier
	s_add_i32 s95, 32, 0x1c000
	s_add_i32 s2, s94, s5
	v_add_u32_e32 v131, s95, v145
	s_mov_b32 m0, s2
	ds_read_b128 v[222:225], v131
	ds_read_b128 v[226:229], v131 offset:1024
	ds_read_b128 v[230:233], v131 offset:2048
	ds_read_b128 v[234:237], v131 offset:3072
	s_add_u32 s100, s16, 128
	s_addc_u32 s101, s17, 0
	global_load_lds_dwordx4 v154, s[100:101]
	s_add_i32 m0, s2, 0x2000
	s_nop 0
	global_load_lds_dwordx4 v138, s[100:101]
	s_barrier
	s_waitcnt lgkmcnt(0)
	s_waitcnt lgkmcnt(0)
	v_mfma_f32_16x16x32_bf16 v[118:121], v[222:225], v[190:193], v[118:121]
	v_mfma_f32_16x16x32_bf16 v[114:117], v[230:233], v[190:193], v[114:117]
	v_mfma_f32_16x16x32_bf16 v[102:105], v[222:225], v[198:201], v[102:105]
	v_mfma_f32_16x16x32_bf16 v[98:101], v[230:233], v[198:201], v[98:101]
	v_mfma_f32_16x16x32_bf16 v[86:89], v[222:225], v[206:209], v[86:89]
	v_mfma_f32_16x16x32_bf16 v[82:85], v[230:233], v[206:209], v[82:85]
	v_mfma_f32_16x16x32_bf16 v[70:73], v[222:225], v[214:217], v[70:73]
	v_mfma_f32_16x16x32_bf16 v[66:69], v[230:233], v[214:217], v[66:69]
	v_mfma_f32_16x16x32_bf16 v[118:121], v[226:229], v[194:197], v[118:121]
	v_mfma_f32_16x16x32_bf16 v[114:117], v[234:237], v[194:197], v[114:117]
	v_mfma_f32_16x16x32_bf16 v[102:105], v[226:229], v[202:205], v[102:105]
	v_mfma_f32_16x16x32_bf16 v[98:101], v[234:237], v[202:205], v[98:101]
	v_mfma_f32_16x16x32_bf16 v[86:89], v[226:229], v[210:213], v[86:89]
	v_mfma_f32_16x16x32_bf16 v[82:85], v[234:237], v[210:213], v[82:85]
	v_mfma_f32_16x16x32_bf16 v[70:73], v[226:229], v[218:221], v[70:73]
	v_mfma_f32_16x16x32_bf16 v[66:69], v[234:237], v[218:221], v[66:69]
	s_mov_b32 m0, s21
	s_barrier
	ds_read_b128 v[190:193], v151 offset:49152
	ds_read_b128 v[194:197], v151 offset:50176
	ds_read_b128 v[198:201], v151 offset:51200
	ds_read_b128 v[202:205], v151 offset:52224
	ds_read_b128 v[206:209], v151 offset:53248
	ds_read_b128 v[210:213], v151 offset:54272
	ds_read_b128 v[214:217], v151 offset:55296
	ds_read_b128 v[218:221], v151 offset:56320
	s_add_u32 s98, s98, 128
	s_addc_u32 s99, s99, 0
	global_load_lds_dwordx4 v134, s[98:99]
	s_mov_b32 m0, s22
	s_nop 0
	global_load_lds_dwordx4 v136, s[98:99]
	s_barrier
	s_waitcnt lgkmcnt(0)
	s_waitcnt lgkmcnt(0)
	v_mfma_f32_16x16x32_bf16 v[62:65], v[170:173], v[190:193], v[62:65]
	v_mfma_f32_16x16x32_bf16 v[58:61], v[182:185], v[190:193], v[58:61]
	v_mfma_f32_16x16x32_bf16 v[46:49], v[170:173], v[198:201], v[46:49]
	v_mfma_f32_16x16x32_bf16 v[42:45], v[182:185], v[198:201], v[42:45]
	v_mfma_f32_16x16x32_bf16 v[30:33], v[170:173], v[206:209], v[30:33]
	v_mfma_f32_16x16x32_bf16 v[26:29], v[182:185], v[206:209], v[26:29]
	v_mfma_f32_16x16x32_bf16 v[14:17], v[170:173], v[214:217], v[14:17]
	v_mfma_f32_16x16x32_bf16 v[10:13], v[182:185], v[214:217], v[10:13]
	v_mfma_f32_16x16x32_bf16 v[62:65], v[174:177], v[194:197], v[62:65]
	v_mfma_f32_16x16x32_bf16 v[58:61], v[186:189], v[194:197], v[58:61]
	v_mfma_f32_16x16x32_bf16 v[46:49], v[174:177], v[202:205], v[46:49]
	v_mfma_f32_16x16x32_bf16 v[42:45], v[186:189], v[202:205], v[42:45]
	v_mfma_f32_16x16x32_bf16 v[30:33], v[174:177], v[210:213], v[30:33]
	v_mfma_f32_16x16x32_bf16 v[26:29], v[186:189], v[210:213], v[26:29]
	v_mfma_f32_16x16x32_bf16 v[14:17], v[174:177], v[218:221], v[14:17]
	v_mfma_f32_16x16x32_bf16 v[10:13], v[186:189], v[218:221], v[10:13]
	s_barrier
	s_add_u32 s2, s16, 0x40080
	s_addc_u32 s3, s17, 0
	s_add_i32 s16, s95, s5
	s_mov_b32 m0, s16
	s_nop 0
	global_load_lds_dwordx4 v154, s[2:3]
	s_add_i32 m0, s16, 0x2000
	s_nop 0
	global_load_lds_dwordx4 v138, s[2:3]
	s_waitcnt vmcnt(6)
	s_barrier
	v_mfma_f32_16x16x32_bf16 v[54:57], v[222:225], v[190:193], v[54:57]
	v_mfma_f32_16x16x32_bf16 v[50:53], v[230:233], v[190:193], v[50:53]
	v_mfma_f32_16x16x32_bf16 v[38:41], v[222:225], v[198:201], v[38:41]
	v_mfma_f32_16x16x32_bf16 v[34:37], v[230:233], v[198:201], v[34:37]
	v_mfma_f32_16x16x32_bf16 v[22:25], v[222:225], v[206:209], v[22:25]
	v_mfma_f32_16x16x32_bf16 v[18:21], v[230:233], v[206:209], v[18:21]
	v_mfma_f32_16x16x32_bf16 v[6:9], v[222:225], v[214:217], v[6:9]
	v_mfma_f32_16x16x32_bf16 v[2:5], v[230:233], v[214:217], v[2:5]
	v_mfma_f32_16x16x32_bf16 v[54:57], v[226:229], v[194:197], v[54:57]
	v_mfma_f32_16x16x32_bf16 v[50:53], v[234:237], v[194:197], v[50:53]
	v_mfma_f32_16x16x32_bf16 v[38:41], v[226:229], v[202:205], v[38:41]
	v_mfma_f32_16x16x32_bf16 v[34:37], v[234:237], v[202:205], v[34:37]
	v_mfma_f32_16x16x32_bf16 v[22:25], v[226:229], v[210:213], v[22:25]
	v_mfma_f32_16x16x32_bf16 v[18:21], v[234:237], v[210:213], v[18:21]
	v_mfma_f32_16x16x32_bf16 v[6:9], v[226:229], v[218:221], v[6:9]
	v_mfma_f32_16x16x32_bf16 v[2:5], v[234:237], v[218:221], v[2:5]
	s_add_i32 s39, s39, 2
	s_add_u32 s30, s30, 0x100
	s_addc_u32 s31, s31, 0
	s_add_u32 s28, s28, 0x100
	s_addc_u32 s29, s29, 0
	s_cmp_gt_u32 s39, 13
	s_barrier
.LBB0_620:
	s_add_u32 s2, s30, 0xfffc0080
	s_addc_u32 s3, s31, -1
	s_add_i32 s94, 32, 0x10000
	v_add_u32_e32 v131, s94, v145
	ds_read_b128 v[170:173], v131
	ds_read_b128 v[174:177], v131 offset:1024
	ds_read_b128 v[182:185], v131 offset:2048
	ds_read_b128 v[186:189], v131 offset:3072
	s_cmp_eq_u32 s39, 12
	s_cselect_b32 s3, s11, s3
	s_cselect_b32 s2, s18, s2
	s_cselect_b32 s17, s13, s29
	s_cselect_b32 s16, s19, s28
	s_add_i32 m0, s35, 0xc000
	ds_read_b128 v[190:193], v151
	ds_read_b128 v[194:197], v151 offset:1024
	ds_read_b128 v[198:201], v151 offset:2048
	ds_read_b128 v[202:205], v151 offset:3072
	ds_read_b128 v[206:209], v151 offset:4096
	ds_read_b128 v[210:213], v151 offset:5120
	ds_read_b128 v[214:217], v151 offset:6144
	ds_read_b128 v[218:221], v151 offset:7168
	global_load_lds_dwordx4 v140, s[30:31]
	s_add_i32 m0, s35, 0xe000
	s_nop 0
	global_load_lds_dwordx4 v142, s[30:31]
	s_waitcnt lgkmcnt(8)
	s_barrier
	s_waitcnt lgkmcnt(0)
	s_waitcnt lgkmcnt(0)
	v_mfma_f32_16x16x32_bf16 v[126:129], v[170:173], v[190:193], v[126:129]
	v_mfma_f32_16x16x32_bf16 v[122:125], v[182:185], v[190:193], v[122:125]
	v_mfma_f32_16x16x32_bf16 v[110:113], v[170:173], v[198:201], v[110:113]
	v_mfma_f32_16x16x32_bf16 v[106:109], v[182:185], v[198:201], v[106:109]
	v_mfma_f32_16x16x32_bf16 v[94:97], v[170:173], v[206:209], v[94:97]
	v_mfma_f32_16x16x32_bf16 v[90:93], v[182:185], v[206:209], v[90:93]
	v_mfma_f32_16x16x32_bf16 v[78:81], v[170:173], v[214:217], v[78:81]
	v_mfma_f32_16x16x32_bf16 v[74:77], v[182:185], v[214:217], v[74:77]
	v_mfma_f32_16x16x32_bf16 v[126:129], v[174:177], v[194:197], v[126:129]
	v_mfma_f32_16x16x32_bf16 v[122:125], v[186:189], v[194:197], v[122:125]
	v_mfma_f32_16x16x32_bf16 v[110:113], v[174:177], v[202:205], v[110:113]
	v_mfma_f32_16x16x32_bf16 v[106:109], v[186:189], v[202:205], v[106:109]
	v_mfma_f32_16x16x32_bf16 v[94:97], v[174:177], v[210:213], v[94:97]
	v_mfma_f32_16x16x32_bf16 v[90:93], v[186:189], v[210:213], v[90:93]
	v_mfma_f32_16x16x32_bf16 v[78:81], v[174:177], v[218:221], v[78:81]
	v_mfma_f32_16x16x32_bf16 v[74:77], v[186:189], v[218:221], v[74:77]
	s_barrier
	s_add_i32 vcc_lo, 32, 0x14000
	s_add_i32 s94, s94, s5
	v_add_u32_e32 v131, vcc_lo, v145
	s_mov_b32 m0, s94
	ds_read_b128 v[222:225], v131
	ds_read_b128 v[226:229], v131 offset:1024
	ds_read_b128 v[230:233], v131 offset:2048
	ds_read_b128 v[234:237], v131 offset:3072
	global_load_lds_dwordx4 v154, s[16:17]
	s_add_i32 m0, s94, 0x2000
	s_nop 0
	global_load_lds_dwordx4 v138, s[16:17]
	s_barrier
	s_waitcnt lgkmcnt(0)
	s_waitcnt lgkmcnt(0)
	v_mfma_f32_16x16x32_bf16 v[118:121], v[222:225], v[190:193], v[118:121]
	v_mfma_f32_16x16x32_bf16 v[114:117], v[230:233], v[190:193], v[114:117]
	v_mfma_f32_16x16x32_bf16 v[102:105], v[222:225], v[198:201], v[102:105]
	v_mfma_f32_16x16x32_bf16 v[98:101], v[230:233], v[198:201], v[98:101]
	v_mfma_f32_16x16x32_bf16 v[86:89], v[222:225], v[206:209], v[86:89]
	v_mfma_f32_16x16x32_bf16 v[82:85], v[230:233], v[206:209], v[82:85]
	v_mfma_f32_16x16x32_bf16 v[70:73], v[222:225], v[214:217], v[70:73]
	v_mfma_f32_16x16x32_bf16 v[66:69], v[230:233], v[214:217], v[66:69]
	v_mfma_f32_16x16x32_bf16 v[118:121], v[226:229], v[194:197], v[118:121]
	v_mfma_f32_16x16x32_bf16 v[114:117], v[234:237], v[194:197], v[114:117]
	v_mfma_f32_16x16x32_bf16 v[102:105], v[226:229], v[202:205], v[102:105]
	v_mfma_f32_16x16x32_bf16 v[98:101], v[234:237], v[202:205], v[98:101]
	v_mfma_f32_16x16x32_bf16 v[86:89], v[226:229], v[210:213], v[86:89]
	v_mfma_f32_16x16x32_bf16 v[82:85], v[234:237], v[210:213], v[82:85]
	v_mfma_f32_16x16x32_bf16 v[70:73], v[226:229], v[218:221], v[70:73]
	v_mfma_f32_16x16x32_bf16 v[66:69], v[234:237], v[218:221], v[66:69]
	s_mov_b32 m0, s35
	s_mov_b64 s[98:99], s[2:3]
	s_barrier
	ds_read_b128 v[190:193], v151 offset:16384
	ds_read_b128 v[194:197], v151 offset:17408
	ds_read_b128 v[198:201], v151 offset:18432
	ds_read_b128 v[202:205], v151 offset:19456
	ds_read_b128 v[206:209], v151 offset:20480
	ds_read_b128 v[210:213], v151 offset:21504
	ds_read_b128 v[214:217], v151 offset:22528
	ds_read_b128 v[218:221], v151 offset:23552
	global_load_lds_dwordx4 v134, s[2:3]
	s_mov_b32 m0, s14
	s_nop 0
	global_load_lds_dwordx4 v136, s[2:3]
	s_barrier
	s_waitcnt lgkmcnt(0)
	s_waitcnt lgkmcnt(0)
	v_mfma_f32_16x16x32_bf16 v[62:65], v[170:173], v[190:193], v[62:65]
	v_mfma_f32_16x16x32_bf16 v[58:61], v[182:185], v[190:193], v[58:61]
	v_mfma_f32_16x16x32_bf16 v[46:49], v[170:173], v[198:201], v[46:49]
	v_mfma_f32_16x16x32_bf16 v[42:45], v[182:185], v[198:201], v[42:45]
	v_mfma_f32_16x16x32_bf16 v[30:33], v[170:173], v[206:209], v[30:33]
	v_mfma_f32_16x16x32_bf16 v[26:29], v[182:185], v[206:209], v[26:29]
	v_mfma_f32_16x16x32_bf16 v[14:17], v[170:173], v[214:217], v[14:17]
	v_mfma_f32_16x16x32_bf16 v[10:13], v[182:185], v[214:217], v[10:13]
	v_mfma_f32_16x16x32_bf16 v[62:65], v[174:177], v[194:197], v[62:65]
	v_mfma_f32_16x16x32_bf16 v[58:61], v[186:189], v[194:197], v[58:61]
	v_mfma_f32_16x16x32_bf16 v[46:49], v[174:177], v[202:205], v[46:49]
	v_mfma_f32_16x16x32_bf16 v[42:45], v[186:189], v[202:205], v[42:45]
	v_mfma_f32_16x16x32_bf16 v[30:33], v[174:177], v[210:213], v[30:33]
	v_mfma_f32_16x16x32_bf16 v[26:29], v[186:189], v[210:213], v[26:29]
	v_mfma_f32_16x16x32_bf16 v[14:17], v[174:177], v[218:221], v[14:17]
	v_mfma_f32_16x16x32_bf16 v[10:13], v[186:189], v[218:221], v[10:13]
	s_barrier
	s_add_u32 s94, s16, 0x40000
	s_addc_u32 s95, s17, 0
	s_add_i32 vcc_lo, vcc_lo, s5
	s_mov_b32 m0, vcc_lo
	s_nop 0
	global_load_lds_dwordx4 v154, s[94:95]
	s_add_i32 m0, vcc_lo, 0x2000
	s_nop 0
	global_load_lds_dwordx4 v138, s[94:95]
	s_waitcnt vmcnt(6)
	s_barrier
	v_mfma_f32_16x16x32_bf16 v[54:57], v[222:225], v[190:193], v[54:57]
	v_mfma_f32_16x16x32_bf16 v[50:53], v[230:233], v[190:193], v[50:53]
	v_mfma_f32_16x16x32_bf16 v[38:41], v[222:225], v[198:201], v[38:41]
	v_mfma_f32_16x16x32_bf16 v[34:37], v[230:233], v[198:201], v[34:37]
	v_mfma_f32_16x16x32_bf16 v[22:25], v[222:225], v[206:209], v[22:25]
	v_mfma_f32_16x16x32_bf16 v[18:21], v[230:233], v[206:209], v[18:21]
	v_mfma_f32_16x16x32_bf16 v[6:9], v[222:225], v[214:217], v[6:9]
	v_mfma_f32_16x16x32_bf16 v[2:5], v[230:233], v[214:217], v[2:5]
	v_mfma_f32_16x16x32_bf16 v[54:57], v[226:229], v[194:197], v[54:57]
	v_mfma_f32_16x16x32_bf16 v[50:53], v[234:237], v[194:197], v[50:53]
	v_mfma_f32_16x16x32_bf16 v[38:41], v[226:229], v[202:205], v[38:41]
	v_mfma_f32_16x16x32_bf16 v[34:37], v[234:237], v[202:205], v[34:37]
	v_mfma_f32_16x16x32_bf16 v[22:25], v[226:229], v[210:213], v[22:25]
	v_mfma_f32_16x16x32_bf16 v[18:21], v[234:237], v[210:213], v[18:21]
	v_mfma_f32_16x16x32_bf16 v[6:9], v[226:229], v[218:221], v[6:9]
	v_mfma_f32_16x16x32_bf16 v[2:5], v[234:237], v[218:221], v[2:5]
	s_add_i32 s94, 32, 0x18000
	v_add_u32_e32 v131, s94, v145
	s_barrier
	ds_read_b128 v[170:173], v131
	ds_read_b128 v[174:177], v131 offset:1024
	ds_read_b128 v[182:185], v131 offset:2048
	ds_read_b128 v[186:189], v131 offset:3072
	s_add_u32 s2, s2, 0x40000
	s_addc_u32 s3, s3, 0
	s_mov_b32 m0, s4
	ds_read_b128 v[190:193], v151 offset:32768
	ds_read_b128 v[194:197], v151 offset:33792
	ds_read_b128 v[198:201], v151 offset:34816
	ds_read_b128 v[202:205], v151 offset:35840
	ds_read_b128 v[206:209], v151 offset:36864
	ds_read_b128 v[210:213], v151 offset:37888
	ds_read_b128 v[214:217], v151 offset:38912
	ds_read_b128 v[218:221], v151 offset:39936
	global_load_lds_dwordx4 v134, s[2:3]
	s_mov_b32 m0, s20
	s_nop 0
	global_load_lds_dwordx4 v136, s[2:3]
	s_waitcnt lgkmcnt(8)
	s_barrier
	s_waitcnt lgkmcnt(0)
	s_waitcnt lgkmcnt(0)
	v_mfma_f32_16x16x32_bf16 v[126:129], v[170:173], v[190:193], v[126:129]
	v_mfma_f32_16x16x32_bf16 v[122:125], v[182:185], v[190:193], v[122:125]
	v_mfma_f32_16x16x32_bf16 v[110:113], v[170:173], v[198:201], v[110:113]
	v_mfma_f32_16x16x32_bf16 v[106:109], v[182:185], v[198:201], v[106:109]
	v_mfma_f32_16x16x32_bf16 v[94:97], v[170:173], v[206:209], v[94:97]
	v_mfma_f32_16x16x32_bf16 v[90:93], v[182:185], v[206:209], v[90:93]
	v_mfma_f32_16x16x32_bf16 v[78:81], v[170:173], v[214:217], v[78:81]
	v_mfma_f32_16x16x32_bf16 v[74:77], v[182:185], v[214:217], v[74:77]
	v_mfma_f32_16x16x32_bf16 v[126:129], v[174:177], v[194:197], v[126:129]
	v_mfma_f32_16x16x32_bf16 v[122:125], v[186:189], v[194:197], v[122:125]
	v_mfma_f32_16x16x32_bf16 v[110:113], v[174:177], v[202:205], v[110:113]
	v_mfma_f32_16x16x32_bf16 v[106:109], v[186:189], v[202:205], v[106:109]
	v_mfma_f32_16x16x32_bf16 v[94:97], v[174:177], v[210:213], v[94:97]
	v_mfma_f32_16x16x32_bf16 v[90:93], v[186:189], v[210:213], v[90:93]
	v_mfma_f32_16x16x32_bf16 v[78:81], v[174:177], v[218:221], v[78:81]
	v_mfma_f32_16x16x32_bf16 v[74:77], v[186:189], v[218:221], v[74:77]
	s_barrier
	s_add_i32 s95, 32, 0x1c000
	s_add_i32 s2, s94, s5
	v_add_u32_e32 v131, s95, v145
	s_mov_b32 m0, s2
	ds_read_b128 v[222:225], v131
	ds_read_b128 v[226:229], v131 offset:1024
	ds_read_b128 v[230:233], v131 offset:2048
	ds_read_b128 v[234:237], v131 offset:3072
	s_add_u32 s100, s16, 128
	s_addc_u32 s101, s17, 0
	global_load_lds_dwordx4 v154, s[100:101]
	s_add_i32 m0, s2, 0x2000
	s_nop 0
	global_load_lds_dwordx4 v138, s[100:101]
	s_barrier
	s_waitcnt lgkmcnt(0)
	s_waitcnt lgkmcnt(0)
	v_mfma_f32_16x16x32_bf16 v[118:121], v[222:225], v[190:193], v[118:121]
	v_mfma_f32_16x16x32_bf16 v[114:117], v[230:233], v[190:193], v[114:117]
	v_mfma_f32_16x16x32_bf16 v[102:105], v[222:225], v[198:201], v[102:105]
	v_mfma_f32_16x16x32_bf16 v[98:101], v[230:233], v[198:201], v[98:101]
	v_mfma_f32_16x16x32_bf16 v[86:89], v[222:225], v[206:209], v[86:89]
	v_mfma_f32_16x16x32_bf16 v[82:85], v[230:233], v[206:209], v[82:85]
	v_mfma_f32_16x16x32_bf16 v[70:73], v[222:225], v[214:217], v[70:73]
	v_mfma_f32_16x16x32_bf16 v[66:69], v[230:233], v[214:217], v[66:69]
	v_mfma_f32_16x16x32_bf16 v[118:121], v[226:229], v[194:197], v[118:121]
	v_mfma_f32_16x16x32_bf16 v[114:117], v[234:237], v[194:197], v[114:117]
	v_mfma_f32_16x16x32_bf16 v[102:105], v[226:229], v[202:205], v[102:105]
	v_mfma_f32_16x16x32_bf16 v[98:101], v[234:237], v[202:205], v[98:101]
	v_mfma_f32_16x16x32_bf16 v[86:89], v[226:229], v[210:213], v[86:89]
	v_mfma_f32_16x16x32_bf16 v[82:85], v[234:237], v[210:213], v[82:85]
	v_mfma_f32_16x16x32_bf16 v[70:73], v[226:229], v[218:221], v[70:73]
	v_mfma_f32_16x16x32_bf16 v[66:69], v[234:237], v[218:221], v[66:69]
	s_mov_b32 m0, s21
	s_barrier
	ds_read_b128 v[190:193], v151 offset:49152
	ds_read_b128 v[194:197], v151 offset:50176
	ds_read_b128 v[198:201], v151 offset:51200
	ds_read_b128 v[202:205], v151 offset:52224
	ds_read_b128 v[206:209], v151 offset:53248
	ds_read_b128 v[210:213], v151 offset:54272
	ds_read_b128 v[214:217], v151 offset:55296
	ds_read_b128 v[218:221], v151 offset:56320
	s_add_u32 s98, s98, 128
	s_addc_u32 s99, s99, 0
	global_load_lds_dwordx4 v134, s[98:99]
	s_mov_b32 m0, s22
	s_nop 0
	global_load_lds_dwordx4 v136, s[98:99]
	s_barrier
	s_waitcnt lgkmcnt(0)
	s_waitcnt lgkmcnt(0)
	v_mfma_f32_16x16x32_bf16 v[62:65], v[170:173], v[190:193], v[62:65]
	v_mfma_f32_16x16x32_bf16 v[58:61], v[182:185], v[190:193], v[58:61]
	v_mfma_f32_16x16x32_bf16 v[46:49], v[170:173], v[198:201], v[46:49]
	v_mfma_f32_16x16x32_bf16 v[42:45], v[182:185], v[198:201], v[42:45]
	v_mfma_f32_16x16x32_bf16 v[30:33], v[170:173], v[206:209], v[30:33]
	v_mfma_f32_16x16x32_bf16 v[26:29], v[182:185], v[206:209], v[26:29]
	v_mfma_f32_16x16x32_bf16 v[14:17], v[170:173], v[214:217], v[14:17]
	v_mfma_f32_16x16x32_bf16 v[10:13], v[182:185], v[214:217], v[10:13]
	v_mfma_f32_16x16x32_bf16 v[62:65], v[174:177], v[194:197], v[62:65]
	v_mfma_f32_16x16x32_bf16 v[58:61], v[186:189], v[194:197], v[58:61]
	v_mfma_f32_16x16x32_bf16 v[46:49], v[174:177], v[202:205], v[46:49]
	v_mfma_f32_16x16x32_bf16 v[42:45], v[186:189], v[202:205], v[42:45]
	v_mfma_f32_16x16x32_bf16 v[30:33], v[174:177], v[210:213], v[30:33]
	v_mfma_f32_16x16x32_bf16 v[26:29], v[186:189], v[210:213], v[26:29]
	v_mfma_f32_16x16x32_bf16 v[14:17], v[174:177], v[218:221], v[14:17]
	v_mfma_f32_16x16x32_bf16 v[10:13], v[186:189], v[218:221], v[10:13]
	s_barrier
	s_add_u32 s2, s16, 0x40080
	s_addc_u32 s3, s17, 0
	s_add_i32 s16, s95, s5
	s_mov_b32 m0, s16
	s_nop 0
	global_load_lds_dwordx4 v154, s[2:3]
	s_add_i32 m0, s16, 0x2000
	s_nop 0
	global_load_lds_dwordx4 v138, s[2:3]
	s_waitcnt vmcnt(6)
	s_barrier
	v_mfma_f32_16x16x32_bf16 v[54:57], v[222:225], v[190:193], v[54:57]
	v_mfma_f32_16x16x32_bf16 v[50:53], v[230:233], v[190:193], v[50:53]
	v_mfma_f32_16x16x32_bf16 v[38:41], v[222:225], v[198:201], v[38:41]
	v_mfma_f32_16x16x32_bf16 v[34:37], v[230:233], v[198:201], v[34:37]
	v_mfma_f32_16x16x32_bf16 v[22:25], v[222:225], v[206:209], v[22:25]
	v_mfma_f32_16x16x32_bf16 v[18:21], v[230:233], v[206:209], v[18:21]
	v_mfma_f32_16x16x32_bf16 v[6:9], v[222:225], v[214:217], v[6:9]
	v_mfma_f32_16x16x32_bf16 v[2:5], v[230:233], v[214:217], v[2:5]
	v_mfma_f32_16x16x32_bf16 v[54:57], v[226:229], v[194:197], v[54:57]
	v_mfma_f32_16x16x32_bf16 v[50:53], v[234:237], v[194:197], v[50:53]
	v_mfma_f32_16x16x32_bf16 v[38:41], v[226:229], v[202:205], v[38:41]
	v_mfma_f32_16x16x32_bf16 v[34:37], v[234:237], v[202:205], v[34:37]
	v_mfma_f32_16x16x32_bf16 v[22:25], v[226:229], v[210:213], v[22:25]
	v_mfma_f32_16x16x32_bf16 v[18:21], v[234:237], v[210:213], v[18:21]
	v_mfma_f32_16x16x32_bf16 v[6:9], v[226:229], v[218:221], v[6:9]
	v_mfma_f32_16x16x32_bf16 v[2:5], v[234:237], v[218:221], v[2:5]
	s_add_i32 s39, s39, 2
	s_add_u32 s30, s30, 0x100
	s_addc_u32 s31, s31, 0
	s_add_u32 s28, s28, 0x100
	s_addc_u32 s29, s29, 0
	s_cmp_gt_u32 s39, 13
	s_barrier
	s_cbranch_scc0 .LBB0_620
	s_cmp_gt_i32 s10, 2
	s_cselect_b64 s[94:95], -1, 0
	s_mov_b64 s[28:29], -1
	s_and_b64 vcc, exec, s[94:95]
	s_cbranch_vccz .LBB0_638
	s_cmp_gt_u32 s10, 5
	s_mov_b64 s[30:31], -1
	s_cbranch_scc0 .LBB0_636
	s_cmp_gt_u32 s10, 8
	s_cbranch_scc0 .LBB0_633
	s_cmp_gt_u32 s10, 10
	s_mov_b64 s[2:3], -1
	s_cbranch_scc0 .LBB0_631
	s_cmp_lt_i32 s10, 12
	s_mov_b64 s[2:3], 0
	s_cbranch_scc1 .LBB0_630
	s_cmp_lg_u32 s10, 12
	s_mov_b64 s[16:17], -1
	s_cbranch_scc0 .LBB0_628
	s_mov_b64 s[16:17], 0

.LBB0_934:
	s_ashr_i32 s31, s30, 31
	v_cmp_lt_i64_e32 vcc, s[12:13], v[162:163]
	s_lshl_b64 s[12:13], s[30:31], 19
	s_add_u32 s94, s62, s12
	s_addc_u32 s95, s63, s13
	s_and_b64 s[12:13], vcc, exec
	s_cselect_b32 s31, s95, s3
	s_cselect_b32 s4, s94, s2
	s_ashr_i32 s11, s10, 31
	s_lshl_b64 s[12:13], s[10:11], 19
	s_add_u32 s16, s5, s12
	s_addc_u32 s17, s6, s13
	s_and_b64 s[12:13], vcc, exec
	s_cselect_b32 s11, s17, s35
	s_cselect_b32 vcc_lo, s16, s34
	s_add_u32 s12, s2, 0x40080
	s_addc_u32 s13, s3, 0
	s_add_u32 s34, s34, 0x100
	s_addc_u32 s35, s35, 0
	s_mov_b32 vcc_hi, -2
	s_waitcnt lgkmcnt(0)
	s_add_u32 s2, s12, 0xfffc0080
	s_addc_u32 s3, s13, -1
	s_add_i32 s38, 32, 0x10000
	v_add_u32_e32 v152, s38, v145
	ds_read_b128 v[140:143], v152
	ds_read_b128 v[148:151], v152 offset:1024
	ds_read_b128 v[164:167], v152 offset:2048
	ds_read_b128 v[168:171], v152 offset:3072
	s_cmp_eq_u32 vcc_hi, 12
	s_cselect_b32 s3, s31, s3
	s_cselect_b32 s2, s4, s2
	s_cselect_b32 s19, s11, s35
	s_cselect_b32 s18, vcc_lo, s34
	s_add_i32 m0, s14, 0xc000
	ds_read_b128 v[172:175], v147
	ds_read_b128 v[176:179], v147 offset:1024
	ds_read_b128 v[182:185], v147 offset:2048
	ds_read_b128 v[186:189], v147 offset:3072
	ds_read_b128 v[190:193], v147 offset:4096
	ds_read_b128 v[194:197], v147 offset:5120
	ds_read_b128 v[198:201], v147 offset:6144
	ds_read_b128 v[202:205], v147 offset:7168
	global_load_lds_dwordx4 v136, s[12:13]
	s_add_i32 m0, s14, 0xe000
	s_nop 0
	global_load_lds_dwordx4 v138, s[12:13]
	s_waitcnt lgkmcnt(8)
	s_barrier
	s_waitcnt lgkmcnt(0)
	s_waitcnt lgkmcnt(0)
	v_mfma_f32_16x16x32_bf16 v[126:129], v[140:143], v[172:175], 0
	v_mfma_f32_16x16x32_bf16 v[122:125], v[164:167], v[172:175], 0
	v_mfma_f32_16x16x32_bf16 v[110:113], v[140:143], v[182:185], 0
	v_mfma_f32_16x16x32_bf16 v[106:109], v[164:167], v[182:185], 0
	v_mfma_f32_16x16x32_bf16 v[94:97], v[140:143], v[190:193], 0
	v_mfma_f32_16x16x32_bf16 v[90:93], v[164:167], v[190:193], 0
	v_mfma_f32_16x16x32_bf16 v[78:81], v[140:143], v[198:201], 0
	v_mfma_f32_16x16x32_bf16 v[74:77], v[164:167], v[198:201], 0
	v_mfma_f32_16x16x32_bf16 v[126:129], v[148:151], v[176:179], v[126:129]
	v_mfma_f32_16x16x32_bf16 v[122:125], v[168:171], v[176:179], v[122:125]
	v_mfma_f32_16x16x32_bf16 v[110:113], v[148:151], v[186:189], v[110:113]
	v_mfma_f32_16x16x32_bf16 v[106:109], v[168:171], v[186:189], v[106:109]
	v_mfma_f32_16x16x32_bf16 v[94:97], v[148:151], v[194:197], v[94:97]
	v_mfma_f32_16x16x32_bf16 v[90:93], v[168:171], v[194:197], v[90:93]
	v_mfma_f32_16x16x32_bf16 v[78:81], v[148:151], v[202:205], v[78:81]
	v_mfma_f32_16x16x32_bf16 v[74:77], v[168:171], v[202:205], v[74:77]
	s_barrier
	s_add_i32 s24, 32, 0x14000
	v_add_u32_e32 v152, s24, v145
	s_add_i32 s38, s38, s7
	ds_read_b128 v[206:209], v152
	ds_read_b128 v[210:213], v152 offset:1024
	ds_read_b128 v[214:217], v152 offset:2048
	ds_read_b128 v[218:221], v152 offset:3072
	s_mov_b32 m0, s38
	s_nop 0
	global_load_lds_dwordx4 v154, s[18:19]
	s_add_i32 m0, s38, 0x2000
	s_nop 0
	global_load_lds_dwordx4 v130, s[18:19]
	s_barrier
	s_waitcnt lgkmcnt(0)
	s_waitcnt lgkmcnt(0)
	v_mfma_f32_16x16x32_bf16 v[118:121], v[206:209], v[172:175], 0
	v_mfma_f32_16x16x32_bf16 v[114:117], v[214:217], v[172:175], 0
	v_mfma_f32_16x16x32_bf16 v[102:105], v[206:209], v[182:185], 0
	v_mfma_f32_16x16x32_bf16 v[98:101], v[214:217], v[182:185], 0
	v_mfma_f32_16x16x32_bf16 v[86:89], v[206:209], v[190:193], 0
	v_mfma_f32_16x16x32_bf16 v[82:85], v[214:217], v[190:193], 0
	v_mfma_f32_16x16x32_bf16 v[70:73], v[206:209], v[198:201], 0
	v_mfma_f32_16x16x32_bf16 v[66:69], v[214:217], v[198:201], 0
	v_mfma_f32_16x16x32_bf16 v[118:121], v[210:213], v[176:179], v[118:121]
	v_mfma_f32_16x16x32_bf16 v[114:117], v[218:221], v[176:179], v[114:117]
	v_mfma_f32_16x16x32_bf16 v[102:105], v[210:213], v[186:189], v[102:105]
	v_mfma_f32_16x16x32_bf16 v[98:101], v[218:221], v[186:189], v[98:101]
	v_mfma_f32_16x16x32_bf16 v[86:89], v[210:213], v[194:197], v[86:89]
	v_mfma_f32_16x16x32_bf16 v[82:85], v[218:221], v[194:197], v[82:85]
	v_mfma_f32_16x16x32_bf16 v[70:73], v[210:213], v[202:205], v[70:73]
	v_mfma_f32_16x16x32_bf16 v[66:69], v[218:221], v[202:205], v[66:69]
	s_mov_b32 m0, s14
	s_mov_b64 s[98:99], s[2:3]
	s_barrier
	ds_read_b128 v[172:175], v147 offset:16384
	ds_read_b128 v[176:179], v147 offset:17408
	ds_read_b128 v[182:185], v147 offset:18432
	ds_read_b128 v[186:189], v147 offset:19456
	ds_read_b128 v[190:193], v147 offset:20480
	ds_read_b128 v[194:197], v147 offset:21504
	ds_read_b128 v[198:201], v147 offset:22528
	ds_read_b128 v[202:205], v147 offset:23552
	global_load_lds_dwordx4 v134, s[2:3]
	s_mov_b32 m0, s20
	s_nop 0
	global_load_lds_dwordx4 v132, s[2:3]
	s_barrier
	s_waitcnt lgkmcnt(0)
	s_waitcnt lgkmcnt(0)
	v_mfma_f32_16x16x32_bf16 v[62:65], v[140:143], v[172:175], 0
	v_mfma_f32_16x16x32_bf16 v[58:61], v[164:167], v[172:175], 0
	v_mfma_f32_16x16x32_bf16 v[46:49], v[140:143], v[182:185], 0
	v_mfma_f32_16x16x32_bf16 v[42:45], v[164:167], v[182:185], 0
	v_mfma_f32_16x16x32_bf16 v[30:33], v[140:143], v[190:193], 0
	v_mfma_f32_16x16x32_bf16 v[26:29], v[164:167], v[190:193], 0
	v_mfma_f32_16x16x32_bf16 v[14:17], v[140:143], v[198:201], 0
	v_mfma_f32_16x16x32_bf16 v[10:13], v[164:167], v[198:201], 0
	v_mfma_f32_16x16x32_bf16 v[62:65], v[148:151], v[176:179], v[62:65]
	v_mfma_f32_16x16x32_bf16 v[58:61], v[168:171], v[176:179], v[58:61]
	v_mfma_f32_16x16x32_bf16 v[46:49], v[148:151], v[186:189], v[46:49]
	v_mfma_f32_16x16x32_bf16 v[42:45], v[168:171], v[186:189], v[42:45]
	v_mfma_f32_16x16x32_bf16 v[30:33], v[148:151], v[194:197], v[30:33]
	v_mfma_f32_16x16x32_bf16 v[26:29], v[168:171], v[194:197], v[26:29]
	v_mfma_f32_16x16x32_bf16 v[14:17], v[148:151], v[202:205], v[14:17]
	v_mfma_f32_16x16x32_bf16 v[10:13], v[168:171], v[202:205], v[10:13]
	s_barrier
	s_add_u32 s38, s18, 0x40000
	s_addc_u32 s39, s19, 0
	s_add_i32 s24, s24, s7
	s_mov_b32 m0, s24
	s_nop 0
	global_load_lds_dwordx4 v154, s[38:39]
	s_add_i32 m0, s24, 0x2000
	s_nop 0
	global_load_lds_dwordx4 v130, s[38:39]
	s_waitcnt vmcnt(6)
	s_barrier
	v_mfma_f32_16x16x32_bf16 v[54:57], v[206:209], v[172:175], 0
	v_mfma_f32_16x16x32_bf16 v[50:53], v[214:217], v[172:175], 0
	v_mfma_f32_16x16x32_bf16 v[38:41], v[206:209], v[182:185], 0
	v_mfma_f32_16x16x32_bf16 v[34:37], v[214:217], v[182:185], 0
	v_mfma_f32_16x16x32_bf16 v[22:25], v[206:209], v[190:193], 0
	v_mfma_f32_16x16x32_bf16 v[18:21], v[214:217], v[190:193], 0
	v_mfma_f32_16x16x32_bf16 v[6:9], v[206:209], v[198:201], 0
	v_mfma_f32_16x16x32_bf16 v[2:5], v[214:217], v[198:201], 0
	v_mfma_f32_16x16x32_bf16 v[54:57], v[210:213], v[176:179], v[54:57]
	v_mfma_f32_16x16x32_bf16 v[50:53], v[218:221], v[176:179], v[50:53]
	v_mfma_f32_16x16x32_bf16 v[38:41], v[210:213], v[186:189], v[38:41]
	v_mfma_f32_16x16x32_bf16 v[34:37], v[218:221], v[186:189], v[34:37]
	v_mfma_f32_16x16x32_bf16 v[22:25], v[210:213], v[194:197], v[22:25]
	v_mfma_f32_16x16x32_bf16 v[18:21], v[218:221], v[194:197], v[18:21]
	v_mfma_f32_16x16x32_bf16 v[6:9], v[210:213], v[202:205], v[6:9]
	v_mfma_f32_16x16x32_bf16 v[2:5], v[218:221], v[202:205], v[2:5]
	s_add_i32 s24, 32, 0x18000
	v_add_u32_e32 v168, s24, v145
	s_barrier
	ds_read_b128 v[140:143], v168
	ds_read_b128 v[148:151], v168 offset:1024
	ds_read_b128 v[164:167], v168 offset:2048
	ds_read_b128 v[168:171], v168 offset:3072
	s_add_u32 s2, s2, 0x40000
	s_addc_u32 s3, s3, 0
	s_mov_b32 m0, s21
	ds_read_b128 v[172:175], v147 offset:32768
	ds_read_b128 v[176:179], v147 offset:33792
	ds_read_b128 v[182:185], v147 offset:34816
	ds_read_b128 v[186:189], v147 offset:35840
	ds_read_b128 v[190:193], v147 offset:36864
	ds_read_b128 v[194:197], v147 offset:37888
	ds_read_b128 v[198:201], v147 offset:38912
	ds_read_b128 v[202:205], v147 offset:39936
	global_load_lds_dwordx4 v134, s[2:3]
	s_mov_b32 m0, s22
	s_nop 0
	global_load_lds_dwordx4 v132, s[2:3]
	s_waitcnt lgkmcnt(8)
	s_barrier
	s_waitcnt lgkmcnt(0)
	s_waitcnt lgkmcnt(0)
	v_mfma_f32_16x16x32_bf16 v[126:129], v[140:143], v[172:175], v[126:129]
	v_mfma_f32_16x16x32_bf16 v[122:125], v[164:167], v[172:175], v[122:125]
	v_mfma_f32_16x16x32_bf16 v[110:113], v[140:143], v[182:185], v[110:113]
	v_mfma_f32_16x16x32_bf16 v[106:109], v[164:167], v[182:185], v[106:109]
	v_mfma_f32_16x16x32_bf16 v[94:97], v[140:143], v[190:193], v[94:97]
	v_mfma_f32_16x16x32_bf16 v[90:93], v[164:167], v[190:193], v[90:93]
	v_mfma_f32_16x16x32_bf16 v[78:81], v[140:143], v[198:201], v[78:81]
	v_mfma_f32_16x16x32_bf16 v[74:77], v[164:167], v[198:201], v[74:77]
	v_mfma_f32_16x16x32_bf16 v[126:129], v[148:151], v[176:179], v[126:129]
	v_mfma_f32_16x16x32_bf16 v[122:125], v[168:171], v[176:179], v[122:125]
	v_mfma_f32_16x16x32_bf16 v[110:113], v[148:151], v[186:189], v[110:113]
	v_mfma_f32_16x16x32_bf16 v[106:109], v[168:171], v[186:189], v[106:109]
	v_mfma_f32_16x16x32_bf16 v[94:97], v[148:151], v[194:197], v[94:97]
	v_mfma_f32_16x16x32_bf16 v[90:93], v[168:171], v[194:197], v[90:93]
	v_mfma_f32_16x16x32_bf16 v[78:81], v[148:151], v[202:205], v[78:81]
	v_mfma_f32_16x16x32_bf16 v[74:77], v[168:171], v[202:205], v[74:77]
	s_barrier
	s_add_i32 s38, 32, 0x1c000
	s_add_i32 s2, s24, s7
	v_add_u32_e32 v218, s38, v145
	s_mov_b32 m0, s2
	ds_read_b128 v[206:209], v218
	ds_read_b128 v[210:213], v218 offset:1024
	ds_read_b128 v[214:217], v218 offset:2048
	ds_read_b128 v[218:221], v218 offset:3072
	s_add_u32 s100, s18, 128
	s_addc_u32 s101, s19, 0
	global_load_lds_dwordx4 v154, s[100:101]
	s_add_i32 m0, s2, 0x2000
	s_nop 0
	global_load_lds_dwordx4 v130, s[100:101]
	s_barrier
	s_waitcnt lgkmcnt(0)
	s_waitcnt lgkmcnt(0)
	v_mfma_f32_16x16x32_bf16 v[118:121], v[206:209], v[172:175], v[118:121]
	v_mfma_f32_16x16x32_bf16 v[114:117], v[214:217], v[172:175], v[114:117]
	v_mfma_f32_16x16x32_bf16 v[102:105], v[206:209], v[182:185], v[102:105]
	v_mfma_f32_16x16x32_bf16 v[98:101], v[214:217], v[182:185], v[98:101]
	v_mfma_f32_16x16x32_bf16 v[86:89], v[206:209], v[190:193], v[86:89]
	v_mfma_f32_16x16x32_bf16 v[82:85], v[214:217], v[190:193], v[82:85]
	v_mfma_f32_16x16x32_bf16 v[70:73], v[206:209], v[198:201], v[70:73]
	v_mfma_f32_16x16x32_bf16 v[66:69], v[214:217], v[198:201], v[66:69]
	v_mfma_f32_16x16x32_bf16 v[118:121], v[210:213], v[176:179], v[118:121]
	v_mfma_f32_16x16x32_bf16 v[114:117], v[218:221], v[176:179], v[114:117]
	v_mfma_f32_16x16x32_bf16 v[102:105], v[210:213], v[186:189], v[102:105]
	v_mfma_f32_16x16x32_bf16 v[98:101], v[218:221], v[186:189], v[98:101]
	v_mfma_f32_16x16x32_bf16 v[86:89], v[210:213], v[194:197], v[86:89]
	v_mfma_f32_16x16x32_bf16 v[82:85], v[218:221], v[194:197], v[82:85]
	v_mfma_f32_16x16x32_bf16 v[70:73], v[210:213], v[202:205], v[70:73]
	v_mfma_f32_16x16x32_bf16 v[66:69], v[218:221], v[202:205], v[66:69]
	s_mov_b32 m0, s23
	s_barrier
	ds_read_b128 v[172:175], v147 offset:49152
	ds_read_b128 v[176:179], v147 offset:50176
	ds_read_b128 v[182:185], v147 offset:51200
	ds_read_b128 v[186:189], v147 offset:52224
	ds_read_b128 v[190:193], v147 offset:53248
	ds_read_b128 v[194:197], v147 offset:54272
	ds_read_b128 v[198:201], v147 offset:55296
	ds_read_b128 v[202:205], v147 offset:56320
	s_add_u32 s98, s98, 128
	s_addc_u32 s99, s99, 0
	global_load_lds_dwordx4 v134, s[98:99]
	s_mov_b32 m0, s28
	s_nop 0
	global_load_lds_dwordx4 v132, s[98:99]
	s_barrier
	s_waitcnt lgkmcnt(0)
	s_waitcnt lgkmcnt(0)
	v_mfma_f32_16x16x32_bf16 v[62:65], v[140:143], v[172:175], v[62:65]
	v_mfma_f32_16x16x32_bf16 v[58:61], v[164:167], v[172:175], v[58:61]
	v_mfma_f32_16x16x32_bf16 v[46:49], v[140:143], v[182:185], v[46:49]
	v_mfma_f32_16x16x32_bf16 v[42:45], v[164:167], v[182:185], v[42:45]
	v_mfma_f32_16x16x32_bf16 v[30:33], v[140:143], v[190:193], v[30:33]
	v_mfma_f32_16x16x32_bf16 v[26:29], v[164:167], v[190:193], v[26:29]
	v_mfma_f32_16x16x32_bf16 v[14:17], v[140:143], v[198:201], v[14:17]
	v_mfma_f32_16x16x32_bf16 v[10:13], v[164:167], v[198:201], v[10:13]
	v_mfma_f32_16x16x32_bf16 v[62:65], v[148:151], v[176:179], v[62:65]
	v_mfma_f32_16x16x32_bf16 v[58:61], v[168:171], v[176:179], v[58:61]
	v_mfma_f32_16x16x32_bf16 v[46:49], v[148:151], v[186:189], v[46:49]
	v_mfma_f32_16x16x32_bf16 v[42:45], v[168:171], v[186:189], v[42:45]
	v_mfma_f32_16x16x32_bf16 v[30:33], v[148:151], v[194:197], v[30:33]
	v_mfma_f32_16x16x32_bf16 v[26:29], v[168:171], v[194:197], v[26:29]
	v_mfma_f32_16x16x32_bf16 v[14:17], v[148:151], v[202:205], v[14:17]
	v_mfma_f32_16x16x32_bf16 v[10:13], v[168:171], v[202:205], v[10:13]
	s_barrier
	s_add_u32 s2, s18, 0x40080
	s_addc_u32 s3, s19, 0
	s_add_i32 s18, s38, s7
	s_mov_b32 m0, s18
	s_nop 0
	global_load_lds_dwordx4 v154, s[2:3]
	s_add_i32 m0, s18, 0x2000
	s_nop 0
	global_load_lds_dwordx4 v130, s[2:3]
	s_waitcnt vmcnt(6)
	s_barrier
	v_mfma_f32_16x16x32_bf16 v[54:57], v[206:209], v[172:175], v[54:57]
	v_mfma_f32_16x16x32_bf16 v[50:53], v[214:217], v[172:175], v[50:53]
	v_mfma_f32_16x16x32_bf16 v[38:41], v[206:209], v[182:185], v[38:41]
	v_mfma_f32_16x16x32_bf16 v[34:37], v[214:217], v[182:185], v[34:37]
	v_mfma_f32_16x16x32_bf16 v[22:25], v[206:209], v[190:193], v[22:25]
	v_mfma_f32_16x16x32_bf16 v[18:21], v[214:217], v[190:193], v[18:21]
	v_mfma_f32_16x16x32_bf16 v[6:9], v[206:209], v[198:201], v[6:9]
	v_mfma_f32_16x16x32_bf16 v[2:5], v[214:217], v[198:201], v[2:5]
	v_mfma_f32_16x16x32_bf16 v[54:57], v[210:213], v[176:179], v[54:57]
	v_mfma_f32_16x16x32_bf16 v[50:53], v[218:221], v[176:179], v[50:53]
	v_mfma_f32_16x16x32_bf16 v[38:41], v[210:213], v[186:189], v[38:41]
	v_mfma_f32_16x16x32_bf16 v[34:37], v[218:221], v[186:189], v[34:37]
	v_mfma_f32_16x16x32_bf16 v[22:25], v[210:213], v[194:197], v[22:25]
	v_mfma_f32_16x16x32_bf16 v[18:21], v[218:221], v[194:197], v[18:21]
	v_mfma_f32_16x16x32_bf16 v[6:9], v[210:213], v[202:205], v[6:9]
	v_mfma_f32_16x16x32_bf16 v[2:5], v[218:221], v[202:205], v[2:5]
	s_add_i32 vcc_hi, vcc_hi, 2
	s_add_u32 s12, s12, 0x100
	s_addc_u32 s13, s13, 0
	s_add_u32 s34, s34, 0x100
	s_addc_u32 s35, s35, 0
	s_cmp_gt_u32 vcc_hi, 13
	s_barrier
.LBB0_935:
	s_add_u32 s2, s12, 0xfffc0080
	s_addc_u32 s3, s13, -1
	s_add_i32 s38, 32, 0x10000
	v_add_u32_e32 v152, s38, v145
	ds_read_b128 v[140:143], v152
	ds_read_b128 v[148:151], v152 offset:1024
	ds_read_b128 v[164:167], v152 offset:2048
	ds_read_b128 v[168:171], v152 offset:3072
	s_cmp_eq_u32 vcc_hi, 12
	s_cselect_b32 s3, s31, s3
	s_cselect_b32 s2, s4, s2
	s_cselect_b32 s19, s11, s35
	s_cselect_b32 s18, vcc_lo, s34
	s_add_i32 m0, s14, 0xc000
	ds_read_b128 v[172:175], v147
	ds_read_b128 v[176:179], v147 offset:1024
	ds_read_b128 v[182:185], v147 offset:2048
	ds_read_b128 v[186:189], v147 offset:3072
	ds_read_b128 v[190:193], v147 offset:4096
	ds_read_b128 v[194:197], v147 offset:5120
	ds_read_b128 v[198:201], v147 offset:6144
	ds_read_b128 v[202:205], v147 offset:7168
	global_load_lds_dwordx4 v136, s[12:13]
	s_add_i32 m0, s14, 0xe000
	s_nop 0
	global_load_lds_dwordx4 v138, s[12:13]
	s_waitcnt lgkmcnt(8)
	s_barrier
	s_waitcnt lgkmcnt(0)
	s_waitcnt lgkmcnt(0)
	v_mfma_f32_16x16x32_bf16 v[126:129], v[140:143], v[172:175], v[126:129]
	v_mfma_f32_16x16x32_bf16 v[122:125], v[164:167], v[172:175], v[122:125]
	v_mfma_f32_16x16x32_bf16 v[110:113], v[140:143], v[182:185], v[110:113]
	v_mfma_f32_16x16x32_bf16 v[106:109], v[164:167], v[182:185], v[106:109]
	v_mfma_f32_16x16x32_bf16 v[94:97], v[140:143], v[190:193], v[94:97]
	v_mfma_f32_16x16x32_bf16 v[90:93], v[164:167], v[190:193], v[90:93]
	v_mfma_f32_16x16x32_bf16 v[78:81], v[140:143], v[198:201], v[78:81]
	v_mfma_f32_16x16x32_bf16 v[74:77], v[164:167], v[198:201], v[74:77]
	v_mfma_f32_16x16x32_bf16 v[126:129], v[148:151], v[176:179], v[126:129]
	v_mfma_f32_16x16x32_bf16 v[122:125], v[168:171], v[176:179], v[122:125]
	v_mfma_f32_16x16x32_bf16 v[110:113], v[148:151], v[186:189], v[110:113]
	v_mfma_f32_16x16x32_bf16 v[106:109], v[168:171], v[186:189], v[106:109]
	v_mfma_f32_16x16x32_bf16 v[94:97], v[148:151], v[194:197], v[94:97]
	v_mfma_f32_16x16x32_bf16 v[90:93], v[168:171], v[194:197], v[90:93]
	v_mfma_f32_16x16x32_bf16 v[78:81], v[148:151], v[202:205], v[78:81]
	v_mfma_f32_16x16x32_bf16 v[74:77], v[168:171], v[202:205], v[74:77]
	s_barrier
	s_add_i32 s24, 32, 0x14000
	v_add_u32_e32 v152, s24, v145
	s_add_i32 s38, s38, s7
	ds_read_b128 v[206:209], v152
	ds_read_b128 v[210:213], v152 offset:1024
	ds_read_b128 v[214:217], v152 offset:2048
	ds_read_b128 v[218:221], v152 offset:3072
	s_mov_b32 m0, s38
	s_nop 0
	global_load_lds_dwordx4 v154, s[18:19]
	s_add_i32 m0, s38, 0x2000
	s_nop 0
	global_load_lds_dwordx4 v130, s[18:19]
	s_barrier
	s_waitcnt lgkmcnt(0)
	s_waitcnt lgkmcnt(0)
	v_mfma_f32_16x16x32_bf16 v[118:121], v[206:209], v[172:175], v[118:121]
	v_mfma_f32_16x16x32_bf16 v[114:117], v[214:217], v[172:175], v[114:117]
	v_mfma_f32_16x16x32_bf16 v[102:105], v[206:209], v[182:185], v[102:105]
	v_mfma_f32_16x16x32_bf16 v[98:101], v[214:217], v[182:185], v[98:101]
	v_mfma_f32_16x16x32_bf16 v[86:89], v[206:209], v[190:193], v[86:89]
	v_mfma_f32_16x16x32_bf16 v[82:85], v[214:217], v[190:193], v[82:85]
	v_mfma_f32_16x16x32_bf16 v[70:73], v[206:209], v[198:201], v[70:73]
	v_mfma_f32_16x16x32_bf16 v[66:69], v[214:217], v[198:201], v[66:69]
	v_mfma_f32_16x16x32_bf16 v[118:121], v[210:213], v[176:179], v[118:121]
	v_mfma_f32_16x16x32_bf16 v[114:117], v[218:221], v[176:179], v[114:117]
	v_mfma_f32_16x16x32_bf16 v[102:105], v[210:213], v[186:189], v[102:105]
	v_mfma_f32_16x16x32_bf16 v[98:101], v[218:221], v[186:189], v[98:101]
	v_mfma_f32_16x16x32_bf16 v[86:89], v[210:213], v[194:197], v[86:89]
	v_mfma_f32_16x16x32_bf16 v[82:85], v[218:221], v[194:197], v[82:85]
	v_mfma_f32_16x16x32_bf16 v[70:73], v[210:213], v[202:205], v[70:73]
	v_mfma_f32_16x16x32_bf16 v[66:69], v[218:221], v[202:205], v[66:69]
	s_mov_b32 m0, s14
	s_mov_b64 s[98:99], s[2:3]
	s_barrier
	ds_read_b128 v[172:175], v147 offset:16384
	ds_read_b128 v[176:179], v147 offset:17408
	ds_read_b128 v[182:185], v147 offset:18432
	ds_read_b128 v[186:189], v147 offset:19456
	ds_read_b128 v[190:193], v147 offset:20480
	ds_read_b128 v[194:197], v147 offset:21504
	ds_read_b128 v[198:201], v147 offset:22528
	ds_read_b128 v[202:205], v147 offset:23552
	global_load_lds_dwordx4 v134, s[2:3]
	s_mov_b32 m0, s20
	s_nop 0
	global_load_lds_dwordx4 v132, s[2:3]
	s_barrier
	s_waitcnt lgkmcnt(0)
	s_waitcnt lgkmcnt(0)
	v_mfma_f32_16x16x32_bf16 v[62:65], v[140:143], v[172:175], v[62:65]
	v_mfma_f32_16x16x32_bf16 v[58:61], v[164:167], v[172:175], v[58:61]
	v_mfma_f32_16x16x32_bf16 v[46:49], v[140:143], v[182:185], v[46:49]
	v_mfma_f32_16x16x32_bf16 v[42:45], v[164:167], v[182:185], v[42:45]
	v_mfma_f32_16x16x32_bf16 v[30:33], v[140:143], v[190:193], v[30:33]
	v_mfma_f32_16x16x32_bf16 v[26:29], v[164:167], v[190:193], v[26:29]
	v_mfma_f32_16x16x32_bf16 v[14:17], v[140:143], v[198:201], v[14:17]
	v_mfma_f32_16x16x32_bf16 v[10:13], v[164:167], v[198:201], v[10:13]
	v_mfma_f32_16x16x32_bf16 v[62:65], v[148:151], v[176:179], v[62:65]
	v_mfma_f32_16x16x32_bf16 v[58:61], v[168:171], v[176:179], v[58:61]
	v_mfma_f32_16x16x32_bf16 v[46:49], v[148:151], v[186:189], v[46:49]
	v_mfma_f32_16x16x32_bf16 v[42:45], v[168:171], v[186:189], v[42:45]
	v_mfma_f32_16x16x32_bf16 v[30:33], v[148:151], v[194:197], v[30:33]
	v_mfma_f32_16x16x32_bf16 v[26:29], v[168:171], v[194:197], v[26:29]
	v_mfma_f32_16x16x32_bf16 v[14:17], v[148:151], v[202:205], v[14:17]
	v_mfma_f32_16x16x32_bf16 v[10:13], v[168:171], v[202:205], v[10:13]
	s_barrier
	s_add_u32 s38, s18, 0x40000
	s_addc_u32 s39, s19, 0
	s_add_i32 s24, s24, s7
	s_mov_b32 m0, s24
	s_nop 0
	global_load_lds_dwordx4 v154, s[38:39]
	s_add_i32 m0, s24, 0x2000
	s_nop 0
	global_load_lds_dwordx4 v130, s[38:39]
	s_waitcnt vmcnt(6)
	s_barrier
	v_mfma_f32_16x16x32_bf16 v[54:57], v[206:209], v[172:175], v[54:57]
	v_mfma_f32_16x16x32_bf16 v[50:53], v[214:217], v[172:175], v[50:53]
	v_mfma_f32_16x16x32_bf16 v[38:41], v[206:209], v[182:185], v[38:41]
	v_mfma_f32_16x16x32_bf16 v[34:37], v[214:217], v[182:185], v[34:37]
	v_mfma_f32_16x16x32_bf16 v[22:25], v[206:209], v[190:193], v[22:25]
	v_mfma_f32_16x16x32_bf16 v[18:21], v[214:217], v[190:193], v[18:21]
	v_mfma_f32_16x16x32_bf16 v[6:9], v[206:209], v[198:201], v[6:9]
	v_mfma_f32_16x16x32_bf16 v[2:5], v[214:217], v[198:201], v[2:5]
	v_mfma_f32_16x16x32_bf16 v[54:57], v[210:213], v[176:179], v[54:57]
	v_mfma_f32_16x16x32_bf16 v[50:53], v[218:221], v[176:179], v[50:53]
	v_mfma_f32_16x16x32_bf16 v[38:41], v[210:213], v[186:189], v[38:41]
	v_mfma_f32_16x16x32_bf16 v[34:37], v[218:221], v[186:189], v[34:37]
	v_mfma_f32_16x16x32_bf16 v[22:25], v[210:213], v[194:197], v[22:25]
	v_mfma_f32_16x16x32_bf16 v[18:21], v[218:221], v[194:197], v[18:21]
	v_mfma_f32_16x16x32_bf16 v[6:9], v[210:213], v[202:205], v[6:9]
	v_mfma_f32_16x16x32_bf16 v[2:5], v[218:221], v[202:205], v[2:5]
	s_add_i32 s24, 32, 0x18000
	v_add_u32_e32 v168, s24, v145
	s_barrier
	ds_read_b128 v[140:143], v168
	ds_read_b128 v[148:151], v168 offset:1024
	ds_read_b128 v[164:167], v168 offset:2048
	ds_read_b128 v[168:171], v168 offset:3072
	s_add_u32 s2, s2, 0x40000
	s_addc_u32 s3, s3, 0
	s_mov_b32 m0, s21
	ds_read_b128 v[172:175], v147 offset:32768
	ds_read_b128 v[176:179], v147 offset:33792
	ds_read_b128 v[182:185], v147 offset:34816
	ds_read_b128 v[186:189], v147 offset:35840
	ds_read_b128 v[190:193], v147 offset:36864
	ds_read_b128 v[194:197], v147 offset:37888
	ds_read_b128 v[198:201], v147 offset:38912
	ds_read_b128 v[202:205], v147 offset:39936
	global_load_lds_dwordx4 v134, s[2:3]
	s_mov_b32 m0, s22
	s_nop 0
	global_load_lds_dwordx4 v132, s[2:3]
	s_waitcnt lgkmcnt(8)
	s_barrier
	s_waitcnt lgkmcnt(0)
	s_waitcnt lgkmcnt(0)
	v_mfma_f32_16x16x32_bf16 v[126:129], v[140:143], v[172:175], v[126:129]
	v_mfma_f32_16x16x32_bf16 v[122:125], v[164:167], v[172:175], v[122:125]
	v_mfma_f32_16x16x32_bf16 v[110:113], v[140:143], v[182:185], v[110:113]
	v_mfma_f32_16x16x32_bf16 v[106:109], v[164:167], v[182:185], v[106:109]
	v_mfma_f32_16x16x32_bf16 v[94:97], v[140:143], v[190:193], v[94:97]
	v_mfma_f32_16x16x32_bf16 v[90:93], v[164:167], v[190:193], v[90:93]
	v_mfma_f32_16x16x32_bf16 v[78:81], v[140:143], v[198:201], v[78:81]
	v_mfma_f32_16x16x32_bf16 v[74:77], v[164:167], v[198:201], v[74:77]
	v_mfma_f32_16x16x32_bf16 v[126:129], v[148:151], v[176:179], v[126:129]
	v_mfma_f32_16x16x32_bf16 v[122:125], v[168:171], v[176:179], v[122:125]
	v_mfma_f32_16x16x32_bf16 v[110:113], v[148:151], v[186:189], v[110:113]
	v_mfma_f32_16x16x32_bf16 v[106:109], v[168:171], v[186:189], v[106:109]
	v_mfma_f32_16x16x32_bf16 v[94:97], v[148:151], v[194:197], v[94:97]
	v_mfma_f32_16x16x32_bf16 v[90:93], v[168:171], v[194:197], v[90:93]
	v_mfma_f32_16x16x32_bf16 v[78:81], v[148:151], v[202:205], v[78:81]
	v_mfma_f32_16x16x32_bf16 v[74:77], v[168:171], v[202:205], v[74:77]
	s_barrier
	s_add_i32 s38, 32, 0x1c000
	s_add_i32 s2, s24, s7
	v_add_u32_e32 v218, s38, v145
	s_mov_b32 m0, s2
	ds_read_b128 v[206:209], v218
	ds_read_b128 v[210:213], v218 offset:1024
	ds_read_b128 v[214:217], v218 offset:2048
	ds_read_b128 v[218:221], v218 offset:3072
	s_add_u32 s100, s18, 128
	s_addc_u32 s101, s19, 0
	global_load_lds_dwordx4 v154, s[100:101]
	s_add_i32 m0, s2, 0x2000
	s_nop 0
	global_load_lds_dwordx4 v130, s[100:101]
	s_barrier
	s_waitcnt lgkmcnt(0)
	s_waitcnt lgkmcnt(0)
	v_mfma_f32_16x16x32_bf16 v[118:121], v[206:209], v[172:175], v[118:121]
	v_mfma_f32_16x16x32_bf16 v[114:117], v[214:217], v[172:175], v[114:117]
	v_mfma_f32_16x16x32_bf16 v[102:105], v[206:209], v[182:185], v[102:105]
	v_mfma_f32_16x16x32_bf16 v[98:101], v[214:217], v[182:185], v[98:101]
	v_mfma_f32_16x16x32_bf16 v[86:89], v[206:209], v[190:193], v[86:89]
	v_mfma_f32_16x16x32_bf16 v[82:85], v[214:217], v[190:193], v[82:85]
	v_mfma_f32_16x16x32_bf16 v[70:73], v[206:209], v[198:201], v[70:73]
	v_mfma_f32_16x16x32_bf16 v[66:69], v[214:217], v[198:201], v[66:69]
	v_mfma_f32_16x16x32_bf16 v[118:121], v[210:213], v[176:179], v[118:121]
	v_mfma_f32_16x16x32_bf16 v[114:117], v[218:221], v[176:179], v[114:117]
	v_mfma_f32_16x16x32_bf16 v[102:105], v[210:213], v[186:189], v[102:105]
	v_mfma_f32_16x16x32_bf16 v[98:101], v[218:221], v[186:189], v[98:101]
	v_mfma_f32_16x16x32_bf16 v[86:89], v[210:213], v[194:197], v[86:89]
	v_mfma_f32_16x16x32_bf16 v[82:85], v[218:221], v[194:197], v[82:85]
	v_mfma_f32_16x16x32_bf16 v[70:73], v[210:213], v[202:205], v[70:73]
	v_mfma_f32_16x16x32_bf16 v[66:69], v[218:221], v[202:205], v[66:69]
	s_mov_b32 m0, s23
	s_barrier
	ds_read_b128 v[172:175], v147 offset:49152
	ds_read_b128 v[176:179], v147 offset:50176
	ds_read_b128 v[182:185], v147 offset:51200
	ds_read_b128 v[186:189], v147 offset:52224
	ds_read_b128 v[190:193], v147 offset:53248
	ds_read_b128 v[194:197], v147 offset:54272
	ds_read_b128 v[198:201], v147 offset:55296
	ds_read_b128 v[202:205], v147 offset:56320
	s_add_u32 s98, s98, 128
	s_addc_u32 s99, s99, 0
	global_load_lds_dwordx4 v134, s[98:99]
	s_mov_b32 m0, s28
	s_nop 0
	global_load_lds_dwordx4 v132, s[98:99]
	s_barrier
	s_waitcnt lgkmcnt(0)
	s_waitcnt lgkmcnt(0)
	v_mfma_f32_16x16x32_bf16 v[62:65], v[140:143], v[172:175], v[62:65]
	v_mfma_f32_16x16x32_bf16 v[58:61], v[164:167], v[172:175], v[58:61]
	v_mfma_f32_16x16x32_bf16 v[46:49], v[140:143], v[182:185], v[46:49]
	v_mfma_f32_16x16x32_bf16 v[42:45], v[164:167], v[182:185], v[42:45]
	v_mfma_f32_16x16x32_bf16 v[30:33], v[140:143], v[190:193], v[30:33]
	v_mfma_f32_16x16x32_bf16 v[26:29], v[164:167], v[190:193], v[26:29]
	v_mfma_f32_16x16x32_bf16 v[14:17], v[140:143], v[198:201], v[14:17]
	v_mfma_f32_16x16x32_bf16 v[10:13], v[164:167], v[198:201], v[10:13]
	v_mfma_f32_16x16x32_bf16 v[62:65], v[148:151], v[176:179], v[62:65]
	v_mfma_f32_16x16x32_bf16 v[58:61], v[168:171], v[176:179], v[58:61]
	v_mfma_f32_16x16x32_bf16 v[46:49], v[148:151], v[186:189], v[46:49]
	v_mfma_f32_16x16x32_bf16 v[42:45], v[168:171], v[186:189], v[42:45]
	v_mfma_f32_16x16x32_bf16 v[30:33], v[148:151], v[194:197], v[30:33]
	v_mfma_f32_16x16x32_bf16 v[26:29], v[168:171], v[194:197], v[26:29]
	v_mfma_f32_16x16x32_bf16 v[14:17], v[148:151], v[202:205], v[14:17]
	v_mfma_f32_16x16x32_bf16 v[10:13], v[168:171], v[202:205], v[10:13]
	s_barrier
	s_add_u32 s2, s18, 0x40080
	s_addc_u32 s3, s19, 0
	s_add_i32 s18, s38, s7
	s_mov_b32 m0, s18
	s_nop 0
	global_load_lds_dwordx4 v154, s[2:3]
	s_add_i32 m0, s18, 0x2000
	s_nop 0
	global_load_lds_dwordx4 v130, s[2:3]
	s_waitcnt vmcnt(6)
	s_barrier
	v_mfma_f32_16x16x32_bf16 v[54:57], v[206:209], v[172:175], v[54:57]
	v_mfma_f32_16x16x32_bf16 v[50:53], v[214:217], v[172:175], v[50:53]
	v_mfma_f32_16x16x32_bf16 v[38:41], v[206:209], v[182:185], v[38:41]
	v_mfma_f32_16x16x32_bf16 v[34:37], v[214:217], v[182:185], v[34:37]
	v_mfma_f32_16x16x32_bf16 v[22:25], v[206:209], v[190:193], v[22:25]
	v_mfma_f32_16x16x32_bf16 v[18:21], v[214:217], v[190:193], v[18:21]
	v_mfma_f32_16x16x32_bf16 v[6:9], v[206:209], v[198:201], v[6:9]
	v_mfma_f32_16x16x32_bf16 v[2:5], v[214:217], v[198:201], v[2:5]
	v_mfma_f32_16x16x32_bf16 v[54:57], v[210:213], v[176:179], v[54:57]
	v_mfma_f32_16x16x32_bf16 v[50:53], v[218:221], v[176:179], v[50:53]
	v_mfma_f32_16x16x32_bf16 v[38:41], v[210:213], v[186:189], v[38:41]
	v_mfma_f32_16x16x32_bf16 v[34:37], v[218:221], v[186:189], v[34:37]
	v_mfma_f32_16x16x32_bf16 v[22:25], v[210:213], v[194:197], v[22:25]
	v_mfma_f32_16x16x32_bf16 v[18:21], v[218:221], v[194:197], v[18:21]
	v_mfma_f32_16x16x32_bf16 v[6:9], v[210:213], v[202:205], v[6:9]
	v_mfma_f32_16x16x32_bf16 v[2:5], v[218:221], v[202:205], v[2:5]
	s_add_i32 vcc_hi, vcc_hi, 2
	s_add_u32 s12, s12, 0x100
	s_addc_u32 s13, s13, 0
	s_add_u32 s34, s34, 0x100
	s_addc_u32 s35, s35, 0
	s_cmp_gt_u32 vcc_hi, 13
	s_barrier
	s_cbranch_scc0 .LBB0_935
	v_lshl_add_u32 v142, s36, 8, v144
	v_ashrrev_i32_e32 v143, 31, v142
	v_lshl_or_b32 v140, s37, 8, v146
	v_lshlrev_b64 v[150:151], 11, v[142:143]
	v_ashrrev_i32_e32 v141, 31, v140
	v_lshl_add_u64 v[150:151], s[58:59], 0, v[150:151]
	v_lshl_add_u64 v[164:165], v[140:141], 1, v[150:151]
	v_mov_b64_e32 v[238:239], v[164:165]
	global_load_dwordx4 v[150:153], v[164:165], off
	s_nop 0
	global_load_dwordx4 v[164:167], v[164:165], off offset:256
	v_add_co_u32_e32 v240, vcc, 0x8000, v238
	s_nop 1
	v_addc_co_u32_e32 v241, vcc, 0, v239, vcc
	global_load_dwordx4 v[182:185], v[240:241], off
	global_load_dwordx4 v[186:189], v[240:241], off offset:256
	v_add_co_u32_e32 v240, vcc, 0x10000, v238
	s_nop 1
	v_addc_co_u32_e32 v241, vcc, 0, v239, vcc
	global_load_dwordx4 v[190:193], v[240:241], off
	global_load_dwordx4 v[194:197], v[240:241], off offset:256
	v_add_co_u32_e32 v240, vcc, 0x18000, v238
	s_nop 1
	v_addc_co_u32_e32 v241, vcc, 0, v239, vcc
	global_load_dwordx4 v[198:201], v[240:241], off
	global_load_dwordx4 v[202:205], v[240:241], off offset:256
	v_add_co_u32_e32 v240, vcc, 0x40000, v238
	s_nop 1
	v_addc_co_u32_e32 v241, vcc, 0, v239, vcc
	global_load_dwordx4 v[206:209], v[240:241], off
	global_load_dwordx4 v[210:213], v[240:241], off offset:256
	v_add_co_u32_e32 v240, vcc, 0x48000, v238
	s_nop 1
	v_addc_co_u32_e32 v241, vcc, 0, v239, vcc
	global_load_dwordx4 v[214:217], v[240:241], off
	global_load_dwordx4 v[218:221], v[240:241], off offset:256
	v_add_co_u32_e32 v240, vcc, 0x50000, v238
	s_nop 1
	v_addc_co_u32_e32 v241, vcc, 0, v239, vcc
	global_load_dwordx4 v[222:225], v[240:241], off
	global_load_dwordx4 v[226:229], v[240:241], off offset:256
	v_add_co_u32_e32 v240, vcc, 0x58000, v238
	s_nop 1
	v_addc_co_u32_e32 v241, vcc, 0, v239, vcc
	global_load_dwordx4 v[230:233], v[240:241], off
	global_load_dwordx4 v[234:237], v[240:241], off offset:256
	v_lshlrev_b32_e32 v148, 1, v140
	s_waitcnt vmcnt(14)
	v_lshlrev_b32_e32 v149, 16, v150
	v_lshlrev_b32_e32 v171, 16, v164
	v_and_b32_e32 v164, 0xffff0000, v164
	v_and_b32_e32 v150, 0xffff0000, v150
	v_lshlrev_b32_e32 v168, 16, v151
	v_and_b32_e32 v151, 0xffff0000, v151
	v_lshlrev_b32_e32 v173, 16, v166
	v_and_b32_e32 v166, 0xffff0000, v166
	v_lshlrev_b32_e32 v174, 16, v167
	v_and_b32_e32 v167, 0xffff0000, v167
	v_add_f32_e32 v118, v118, v171
	v_add_f32_e32 v119, v119, v164
	v_lshlrev_b32_e32 v172, 16, v165
	v_add_f32_e32 v126, v126, v149
	v_add_f32_e32 v149, v114, v173
	v_add_f32_e32 v114, v127, v150
	v_add_f32_e32 v127, v115, v166
	v_add_f32_e32 v115, v128, v168
	v_add_f32_e32 v128, v116, v174
	v_add_f32_e32 v116, v129, v151
	v_add_f32_e32 v129, v117, v167
	v_mul_f32_e32 v117, v118, v118
	v_mul_f32_e32 v150, v119, v119
	v_add_f32_e32 v120, v120, v172
	v_fmac_f32_e32 v117, v126, v126
	v_fmac_f32_e32 v150, v114, v114
	v_and_b32_e32 v165, 0xffff0000, v165
	v_add_f32_e32 v117, v117, v150
	v_mul_f32_e32 v150, v120, v120
	v_add_f32_e32 v121, v121, v165
	v_fmac_f32_e32 v150, v115, v115
	v_add_f32_e32 v117, v150, v117
	v_mul_f32_e32 v150, v121, v121
	v_lshlrev_b32_e32 v169, 16, v152
	v_fmac_f32_e32 v150, v116, v116
	v_add_f32_e32 v122, v122, v169
	v_add_f32_e32 v117, v150, v117
	v_mul_f32_e32 v150, v149, v149
	v_and_b32_e32 v152, 0xffff0000, v152
	v_fmac_f32_e32 v150, v122, v122
	v_add_f32_e32 v123, v123, v152
	v_add_f32_e32 v117, v150, v117
	v_mul_f32_e32 v150, v127, v127
	v_lshlrev_b32_e32 v170, 16, v153
	v_fmac_f32_e32 v150, v123, v123
	v_add_f32_e32 v124, v124, v170
	v_add_f32_e32 v117, v150, v117
	v_mul_f32_e32 v150, v128, v128
	v_and_b32_e32 v153, 0xffff0000, v153
	v_fmac_f32_e32 v150, v124, v124
	v_add_f32_e32 v125, v125, v153
	v_add_f32_e32 v117, v150, v117
	v_mul_f32_e32 v150, v129, v129
	v_fmac_f32_e32 v150, v125, v125
	v_lshl_add_u32 v151, v142, 11, v148
	v_cvt_pk_bf16_f32 v114, v126, v114
	v_cvt_pk_bf16_f32 v115, v115, v116
	v_add_f32_e32 v150, v150, v117
	v_cvt_pk_bf16_f32 v116, v122, v123
	v_cvt_pk_bf16_f32 v117, v124, v125
	buffer_store_dwordx4 v[114:117], v151, s[64:67], 0 offen sc1
	s_nop 1
	v_cvt_pk_bf16_f32 v114, v118, v119
	v_cvt_pk_bf16_f32 v115, v120, v121
	v_cvt_pk_bf16_f32 v116, v149, v127
	v_cvt_pk_bf16_f32 v117, v128, v129
	buffer_store_dwordx4 v[114:117], v151, s[64:67], 0 offen offset:256 sc1
	s_nop 1
	v_and_b32_e32 v115, 64, v181
	v_xor_b32_e32 v114, 16, v181
	v_add_u32_e32 v115, 64, v115
	v_cmp_lt_i32_e32 vcc, v114, v115
	v_xor_b32_e32 v117, 32, v181
	s_nop 0
	v_cndmask_b32_e32 v114, v181, v114, vcc
	v_lshlrev_b32_e32 v116, 2, v114
	ds_bpermute_b32 v114, v116, v150
	v_cmp_lt_i32_e32 vcc, v117, v115
	s_waitcnt lgkmcnt(0)
	v_add_f32_e32 v114, v150, v114
	v_cndmask_b32_e32 v115, v181, v117, vcc
	v_lshlrev_b32_e32 v117, 2, v115
	ds_bpermute_b32 v115, v117, v114
	s_and_saveexec_b64 s[2:3], s[40:41]
	s_cbranch_execz .LBB0_938
	v_lshl_add_u64 v[118:119], v[142:143], 2, s[0:1]
	s_waitcnt lgkmcnt(0)
	v_add_f32_e32 v114, v114, v115
	global_atomic_add_f32 v[118:119], v114, off
